# p4 retention: S-stage K-fragment reads issued up front, PV steps with 3 V-fragment quads in flight
# speedup vs baseline: 1.0198x; 1.0013x over previous
.LBB0_396:
	v_add_f32_e32 v98, -1.0, v97
	v_sub_f32_e32 v99, v98, v97
	v_add_f32_e32 v99, 1.0, v99
	v_sub_f32_e64 v98, -v96, v98
	v_add_f32_e32 v101, v98, v99
	v_cvt_f64_f32_e32 v[98:99], v97
	v_frexp_exp_i32_f64_e32 v98, v[98:99]
	v_subbrev_co_u32_e64 v98, vcc, 0, v98, s[68:69]
	v_sub_u32_e32 v99, 0, v98
	v_ldexp_f32 v97, v97, v99
	v_ldexp_f32 v99, v101, v99
	v_add_f32_e32 v101, -1.0, v97
	v_add_f32_e32 v102, 1.0, v101
	v_sub_f32_e32 v102, v97, v102
	v_add_f32_e32 v102, v99, v102
	v_add_f32_e32 v103, v101, v102
	v_sub_f32_e32 v101, v103, v101
	v_sub_f32_e32 v101, v102, v101
	v_add_f32_e32 v102, 1.0, v97
	v_add_f32_e32 v104, -1.0, v102
	v_sub_f32_e32 v97, v97, v104
	v_add_f32_e32 v97, v99, v97
	v_add_f32_e32 v99, v102, v97
	v_sub_f32_e32 v102, v99, v102
	v_sub_f32_e32 v97, v97, v102
	v_rcp_f32_e32 v102, v99
	v_cvt_f32_i32_e32 v98, v98
	s_mov_b32 s2, 0x3f317218
	v_cmp_nlt_f32_e32 vcc, 1.0, v96
	v_mul_f32_e32 v104, v103, v102
	v_mul_f32_e32 v105, v99, v104
	v_fma_f32 v106, v104, v99, -v105
	v_fmac_f32_e32 v106, v104, v97
	v_add_f32_e32 v107, v105, v106
	v_sub_f32_e32 v108, v103, v107
	v_sub_f32_e32 v103, v103, v108
	v_sub_f32_e32 v105, v107, v105
	v_sub_f32_e32 v103, v103, v107
	v_add_f32_e32 v101, v101, v103
	v_sub_f32_e32 v103, v105, v106
	v_add_f32_e32 v101, v103, v101
	v_add_f32_e32 v103, v108, v101
	v_mul_f32_e32 v105, v102, v103
	v_mul_f32_e32 v106, v99, v105
	v_fma_f32 v99, v105, v99, -v106
	v_fmac_f32_e32 v99, v105, v97
	v_sub_f32_e32 v97, v108, v103
	v_add_f32_e32 v97, v101, v97
	v_add_f32_e32 v101, v106, v99
	v_sub_f32_e32 v107, v103, v101
	v_sub_f32_e32 v103, v103, v107
	v_sub_f32_e32 v106, v101, v106
	v_sub_f32_e32 v101, v103, v101
	v_add_f32_e32 v97, v97, v101
	v_sub_f32_e32 v99, v106, v99
	v_add_f32_e32 v97, v99, v97
	v_add_f32_e32 v99, v104, v105
	v_add_f32_e32 v97, v107, v97
	v_sub_f32_e32 v101, v99, v104
	v_mul_f32_e32 v97, v102, v97
	v_sub_f32_e32 v101, v105, v101
	v_add_f32_e32 v97, v101, v97
	v_add_f32_e32 v101, v99, v97
	v_mul_f32_e32 v104, 0x3f317218, v98
	v_mul_f32_e32 v102, v101, v101
	v_fma_f32 v105, v98, s2, -v104
	v_fmamk_f32 v103, v102, 0x3e9b6dac, v221
	v_fmac_f32_e32 v105, 0xb102e308, v98
	v_sub_f32_e32 v98, v101, v99
	v_fmaak_f32 v103, v102, v103, 0x3f2aaada
	v_sub_f32_e32 v97, v97, v98
	v_ldexp_f32 v98, v101, 1
	v_mul_f32_e32 v101, v101, v102
	v_mul_f32_e32 v101, v101, v103
	v_add_f32_e32 v102, v98, v101
	v_sub_f32_e32 v98, v102, v98
	v_ldexp_f32 v97, v97, 1
	v_sub_f32_e32 v98, v101, v98
	v_add_f32_e32 v97, v97, v98
	v_add_f32_e32 v98, v102, v97
	v_add_f32_e32 v99, v104, v105
	v_sub_f32_e32 v101, v98, v102
	v_sub_f32_e32 v97, v97, v101
	v_add_f32_e32 v101, v99, v98
	v_sub_f32_e32 v102, v101, v99
	v_sub_f32_e32 v104, v99, v104
	v_sub_f32_e32 v103, v101, v102
	v_sub_f32_e32 v104, v105, v104
	v_sub_f32_e32 v99, v99, v103
	v_sub_f32_e32 v98, v98, v102
	v_add_f32_e32 v98, v98, v99
	v_add_f32_e32 v99, v104, v97
	v_sub_f32_e32 v102, v99, v104
	v_add_f32_e32 v98, v99, v98
	v_sub_f32_e32 v103, v99, v102
	v_add_f32_e32 v99, v101, v98
	v_sub_f32_e32 v103, v104, v103
	v_sub_f32_e32 v97, v97, v102
	v_sub_f32_e32 v101, v99, v101
	v_add_f32_e32 v97, v97, v103
	v_sub_f32_e32 v98, v98, v101
	v_add_f32_e32 v97, v97, v98
	v_add_f32_e32 v97, v99, v97
	v_cndmask_b32_e32 v97, v230, v97, vcc
	v_cmp_neq_f32_e32 vcc, 1.0, v96
	s_mov_b32 s2, 0x33800000
	v_xor_b32_e32 v100, 0x80000000, v96
	v_cndmask_b32_e32 v97, v231, v97, vcc
	v_cmp_gt_f32_e32 vcc, s2, v96
	v_add_u32_e32 v104, v180, v181
	s_mov_b64 s[16:17], -1
	v_cndmask_b32_e32 v96, v97, v100, vcc
	v_mul_f32_e32 v143, 0x3fb8aa3b, v96
	ds_read_b128 v[96:99], v104
	ds_read_b128 v[100:103], v104 offset:64
	ds_read_b128 v[108:111], v104 offset:128
	ds_read_b128 v[112:115], v104 offset:192
	s_waitcnt lgkmcnt(3)
	v_mfma_f32_16x16x32_bf16 v[96:99], v[84:87], v[96:99], 0
	s_andn2_b64 vcc, exec, s[10:11]
	s_waitcnt lgkmcnt(2)
	v_mfma_f32_16x16x32_bf16 v[96:99], v[92:95], v[100:103], v[96:99]
	s_waitcnt lgkmcnt(1)
	v_mfma_f32_16x16x32_bf16 v[96:99], v[80:83], v[108:111], v[96:99]
	s_waitcnt lgkmcnt(0)
	v_mfma_f32_16x16x32_bf16 v[96:99], v[88:91], v[112:115], v[96:99]
	v_mul_f32_e32 v100, v143, v184
	v_exp_f32_e32 v100, v100
	s_nop 5
	v_mul_f32_e32 v96, v100, v96
	v_cndmask_b32_e64 v96, 0, v96, s[0:1]
	v_cvt_pk_bf16_f32 v96, v96, v131
	ds_write_b16 v185, v96
	v_mul_f32_e32 v96, v143, v186
	v_exp_f32_e32 v96, v96
	s_nop 0
	v_mul_f32_e32 v96, v96, v97
	v_cndmask_b32_e64 v96, 0, v96, s[4:5]
	v_cvt_pk_bf16_f32 v96, v96, v131
	ds_write_b16 v185, v96 offset:272
	v_mul_f32_e32 v96, v143, v187
	v_exp_f32_e32 v96, v96
	s_nop 0
	v_mul_f32_e32 v96, v96, v98
	v_cndmask_b32_e64 v96, 0, v96, s[6:7]
	v_cvt_pk_bf16_f32 v96, v96, v131
	ds_write_b16 v185, v96 offset:544
	v_mul_f32_e32 v96, v143, v188
	v_exp_f32_e32 v96, v96
	s_nop 0
	v_mul_f32_e32 v96, v96, v99
	v_cndmask_b32_e64 v96, 0, v96, s[8:9]
	v_cvt_pk_bf16_f32 v96, v96, v131
	ds_write_b16 v185, v96 offset:816
	s_cbranch_vccnz .LBB0_398
	ds_read_b128 v[96:99], v232
	ds_read_b128 v[100:103], v232 offset:64
	ds_read_b128 v[108:111], v232 offset:128
	ds_read_b128 v[112:115], v232 offset:192
	v_readlane_b32 s16, v251, 33
	v_readlane_b32 s17, v251, 34
	s_waitcnt lgkmcnt(3)
	v_mfma_f32_16x16x32_bf16 v[96:99], v[84:87], v[96:99], 0
	s_waitcnt lgkmcnt(2)
	v_mfma_f32_16x16x32_bf16 v[96:99], v[92:95], v[100:103], v[96:99]
	s_waitcnt lgkmcnt(1)
	v_mfma_f32_16x16x32_bf16 v[96:99], v[80:83], v[108:111], v[96:99]
	s_waitcnt lgkmcnt(0)
	v_mfma_f32_16x16x32_bf16 v[96:99], v[88:91], v[112:115], v[96:99]
	v_mul_f32_e32 v100, v143, v189
	v_exp_f32_e32 v100, v100
	s_nop 5
	v_mul_f32_e32 v96, v100, v96
	v_cndmask_b32_e64 v96, 0, v96, s[16:17]
	v_cvt_pk_bf16_f32 v96, v96, v131
	ds_write_b16 v185, v96 offset:32
	v_mul_f32_e32 v96, v143, v190
	v_exp_f32_e32 v96, v96
	v_readlane_b32 s16, v251, 35
	v_readlane_b32 s17, v251, 36
	v_mul_f32_e32 v96, v96, v97
	s_nop 0
	v_cndmask_b32_e64 v96, 0, v96, s[16:17]
	v_cvt_pk_bf16_f32 v96, v96, v131
	ds_write_b16 v185, v96 offset:304
	v_mul_f32_e32 v96, v143, v191
	v_exp_f32_e32 v96, v96
	v_readlane_b32 s16, v251, 25
	v_readlane_b32 s17, v251, 26
	v_mul_f32_e32 v96, v96, v98
	s_nop 0
	v_cndmask_b32_e64 v96, 0, v96, s[16:17]
	v_cvt_pk_bf16_f32 v96, v96, v131
	ds_write_b16 v185, v96 offset:576
	v_mul_f32_e32 v96, v143, v192
	v_exp_f32_e32 v96, v96
	v_readlane_b32 s16, v251, 29
	v_readlane_b32 s17, v251, 30
	v_mul_f32_e32 v96, v96, v99
	s_nop 0
	v_cndmask_b32_e64 v96, 0, v96, s[16:17]
	s_mov_b64 s[16:17], 0
	v_cvt_pk_bf16_f32 v96, v96, v131

.LBB0_400:
	ds_write_b16 v185, v96 offset:848
	v_cndmask_b32_e64 v96, 0, 1, s[12:13]
	v_cmp_ne_u32_e64 s[68:69], 1, v96
	s_andn2_b64 vcc, exec, s[12:13]
	s_cbranch_vccnz .LBB0_402
	ds_read_b128 v[96:99], v232 offset:4352
	ds_read_b128 v[100:103], v232 offset:4416
	ds_read_b128 v[108:111], v232 offset:4480
	ds_read_b128 v[112:115], v232 offset:4544
	v_readlane_b32 s16, v251, 27
	v_readlane_b32 s17, v251, 28
	s_waitcnt lgkmcnt(3)
	v_mfma_f32_16x16x32_bf16 v[96:99], v[84:87], v[96:99], 0
	s_waitcnt lgkmcnt(2)
	v_mfma_f32_16x16x32_bf16 v[96:99], v[92:95], v[100:103], v[96:99]
	s_waitcnt lgkmcnt(1)
	v_mfma_f32_16x16x32_bf16 v[96:99], v[80:83], v[108:111], v[96:99]
	s_waitcnt lgkmcnt(0)
	v_mfma_f32_16x16x32_bf16 v[96:99], v[88:91], v[112:115], v[96:99]
	v_mul_f32_e32 v100, v143, v193
	v_exp_f32_e32 v100, v100
	s_nop 5
	v_mul_f32_e32 v96, v100, v96
	v_cndmask_b32_e64 v96, 0, v96, s[16:17]
	v_cvt_pk_bf16_f32 v96, v96, v131
	ds_write_b16 v185, v96 offset:64
	v_mul_f32_e32 v96, v143, v194
	v_exp_f32_e32 v96, v96
	v_readlane_b32 s16, v251, 41
	v_readlane_b32 s17, v251, 42
	v_mul_f32_e32 v96, v96, v97
	s_nop 0
	v_cndmask_b32_e64 v96, 0, v96, s[16:17]
	v_cvt_pk_bf16_f32 v96, v96, v131
	ds_write_b16 v185, v96 offset:336
	v_mul_f32_e32 v96, v143, v195
	v_exp_f32_e32 v96, v96
	v_readlane_b32 s16, v251, 43
	v_readlane_b32 s17, v251, 44
	v_mul_f32_e32 v96, v96, v98
	s_nop 0
	v_cndmask_b32_e64 v96, 0, v96, s[16:17]
	v_cvt_pk_bf16_f32 v96, v96, v131
	ds_write_b16 v185, v96 offset:608
	v_mul_f32_e32 v96, v143, v196
	v_exp_f32_e32 v96, v96
	v_readlane_b32 s16, v251, 45
	v_readlane_b32 s17, v251, 46
	v_mul_f32_e32 v96, v96, v99
	s_nop 0
	v_cndmask_b32_e64 v96, 0, v96, s[16:17]
	v_cvt_pk_bf16_f32 v96, v96, v131
	ds_write_b16 v185, v96 offset:880
.LBB0_402:
	s_andn2_b64 vcc, exec, s[14:15]
	s_cbranch_vccnz .LBB0_404
	ds_read_b128 v[96:99], v232 offset:8704
	ds_read_b128 v[100:103], v232 offset:8768
	ds_read_b128 v[108:111], v232 offset:8832
	ds_read_b128 v[112:115], v232 offset:8896
	v_readlane_b32 s16, v251, 47
	v_readlane_b32 s17, v251, 48
	s_mov_b64 s[70:71], -1
	s_waitcnt lgkmcnt(3)
	v_mfma_f32_16x16x32_bf16 v[96:99], v[84:87], v[96:99], 0
	s_waitcnt lgkmcnt(2)
	v_mfma_f32_16x16x32_bf16 v[96:99], v[92:95], v[100:103], v[96:99]
	s_waitcnt lgkmcnt(1)
	v_mfma_f32_16x16x32_bf16 v[96:99], v[80:83], v[108:111], v[96:99]
	s_waitcnt lgkmcnt(0)
	v_mfma_f32_16x16x32_bf16 v[96:99], v[88:91], v[112:115], v[96:99]
	v_mul_f32_e32 v100, v143, v197
	v_exp_f32_e32 v100, v100
	s_nop 5
	v_mul_f32_e32 v96, v100, v96
	v_cndmask_b32_e64 v96, 0, v96, s[16:17]
	v_cvt_pk_bf16_f32 v96, v96, v131
	ds_write_b16 v185, v96 offset:96
	v_mul_f32_e32 v96, v143, v198
	v_exp_f32_e32 v96, v96
	v_readlane_b32 s16, v251, 49
	v_readlane_b32 s17, v251, 50
	v_mul_f32_e32 v96, v96, v97
	s_nop 0
	v_cndmask_b32_e64 v96, 0, v96, s[16:17]
	v_cvt_pk_bf16_f32 v96, v96, v131
	ds_write_b16 v185, v96 offset:368
	v_mul_f32_e32 v96, v143, v199
	v_exp_f32_e32 v96, v96
	v_readlane_b32 s16, v251, 51
	v_readlane_b32 s17, v251, 52
	v_mul_f32_e32 v96, v96, v98
	s_nop 0
	v_cndmask_b32_e64 v96, 0, v96, s[16:17]
	v_cvt_pk_bf16_f32 v96, v96, v131
	ds_write_b16 v185, v96 offset:640
	v_mul_f32_e32 v96, v143, v200
	v_exp_f32_e32 v96, v96
	v_readlane_b32 s16, v251, 53
	v_readlane_b32 s17, v251, 54
	v_mul_f32_e32 v96, v96, v99
	s_nop 0
	v_cndmask_b32_e64 v96, 0, v96, s[16:17]
	v_cvt_pk_bf16_f32 v96, v96, v131
	s_cbranch_execz .LBB0_405
	s_branch .LBB0_408

.LBB0_411:
	ds_read_b128 v[96:99], v232 offset:17408
	ds_read_b128 v[100:103], v232 offset:17472
	ds_read_b128 v[108:111], v232 offset:17536
	ds_read_b128 v[112:115], v232 offset:17600
	v_readlane_b32 s16, v250, 1
	v_readlane_b32 s17, v250, 2
	s_mov_b64 s[72:73], -1
	s_waitcnt lgkmcnt(3)
	v_mfma_f32_16x16x32_bf16 v[96:99], v[84:87], v[96:99], 0
	s_waitcnt lgkmcnt(2)
	v_mfma_f32_16x16x32_bf16 v[96:99], v[92:95], v[100:103], v[96:99]
	s_waitcnt lgkmcnt(1)
	v_mfma_f32_16x16x32_bf16 v[96:99], v[80:83], v[108:111], v[96:99]
	s_waitcnt lgkmcnt(0)
	v_mfma_f32_16x16x32_bf16 v[96:99], v[88:91], v[112:115], v[96:99]
	v_mul_f32_e32 v100, v143, v205
	v_exp_f32_e32 v100, v100
	s_nop 5
	v_mul_f32_e32 v96, v100, v96
	v_cndmask_b32_e64 v96, 0, v96, s[16:17]
	v_cvt_pk_bf16_f32 v96, v96, v131
	ds_write_b16 v185, v96 offset:160
	v_mul_f32_e32 v96, v143, v206
	v_exp_f32_e32 v96, v96
	v_readlane_b32 s16, v250, 3
	v_readlane_b32 s17, v250, 4
	v_mul_f32_e32 v96, v96, v97
	s_nop 0
	v_cndmask_b32_e64 v96, 0, v96, s[16:17]
	v_cvt_pk_bf16_f32 v96, v96, v131
	ds_write_b16 v185, v96 offset:432
	v_mul_f32_e32 v96, v143, v207
	v_exp_f32_e32 v96, v96
	s_nop 0
	v_mul_f32_e32 v96, v96, v98
	v_cndmask_b32_e64 v96, 0, v96, s[48:49]
	v_cvt_pk_bf16_f32 v96, v96, v131
	ds_write_b16 v185, v96 offset:704
	v_mul_f32_e32 v96, v143, v208
	v_exp_f32_e32 v96, v96
	s_nop 0
	v_mul_f32_e32 v96, v96, v99
	v_cndmask_b32_e64 v96, 0, v96, s[50:51]
	v_cvt_pk_bf16_f32 v96, v96, v131
	s_cbranch_execz .LBB0_415
	s_branch .LBB0_418

.LBB0_413:
	ds_read_b128 v[96:99], v232 offset:13056
	ds_read_b128 v[100:103], v232 offset:13120
	ds_read_b128 v[108:111], v232 offset:13184
	ds_read_b128 v[112:115], v232 offset:13248
	v_readlane_b32 s16, v251, 57
	v_readlane_b32 s17, v251, 58
	s_waitcnt lgkmcnt(3)
	v_mfma_f32_16x16x32_bf16 v[96:99], v[84:87], v[96:99], 0
	s_waitcnt lgkmcnt(2)
	v_mfma_f32_16x16x32_bf16 v[96:99], v[92:95], v[100:103], v[96:99]
	s_waitcnt lgkmcnt(1)
	v_mfma_f32_16x16x32_bf16 v[96:99], v[80:83], v[108:111], v[96:99]
	s_waitcnt lgkmcnt(0)
	v_mfma_f32_16x16x32_bf16 v[96:99], v[88:91], v[112:115], v[96:99]
	v_mul_f32_e32 v100, v143, v201
	v_exp_f32_e32 v100, v100
	s_nop 5
	v_mul_f32_e32 v96, v100, v96
	v_cndmask_b32_e64 v96, 0, v96, s[16:17]
	v_cvt_pk_bf16_f32 v96, v96, v131
	ds_write_b16 v185, v96 offset:128
	v_mul_f32_e32 v96, v143, v202
	v_exp_f32_e32 v96, v96
	v_readlane_b32 s16, v251, 59
	v_readlane_b32 s17, v251, 60
	v_mul_f32_e32 v96, v96, v97
	s_nop 0
	v_cndmask_b32_e64 v96, 0, v96, s[16:17]
	v_cvt_pk_bf16_f32 v96, v96, v131
	ds_write_b16 v185, v96 offset:400
	v_mul_f32_e32 v96, v143, v203
	v_exp_f32_e32 v96, v96
	v_readlane_b32 s16, v251, 61
	v_readlane_b32 s17, v251, 62
	v_mul_f32_e32 v96, v96, v98
	s_nop 0
	v_cndmask_b32_e64 v96, 0, v96, s[16:17]
	v_cvt_pk_bf16_f32 v96, v96, v131
	ds_write_b16 v185, v96 offset:672
	v_mul_f32_e32 v96, v143, v204
	v_exp_f32_e32 v96, v96
	v_readlane_b32 s16, v251, 63
	v_readlane_b32 s17, v250, 0
	v_mul_f32_e32 v96, v96, v99
	s_nop 0
	v_cndmask_b32_e64 v96, 0, v96, s[16:17]
	v_cvt_pk_bf16_f32 v96, v96, v131
	ds_write_b16 v185, v96 offset:944
	s_andn2_b64 vcc, exec, s[20:21]
	s_cbranch_vccz .LBB0_411

.LBB0_421:
	ds_read_b128 v[96:99], v232 offset:26112
	ds_read_b128 v[100:103], v232 offset:26176
	ds_read_b128 v[108:111], v232 offset:26240
	ds_read_b128 v[112:115], v232 offset:26304
	s_mov_b64 s[16:17], -1
	s_waitcnt lgkmcnt(3)
	v_mfma_f32_16x16x32_bf16 v[96:99], v[84:87], v[96:99], 0
	s_waitcnt lgkmcnt(2)
	v_mfma_f32_16x16x32_bf16 v[96:99], v[92:95], v[100:103], v[96:99]
	s_waitcnt lgkmcnt(1)
	v_mfma_f32_16x16x32_bf16 v[96:99], v[80:83], v[108:111], v[96:99]
	s_waitcnt lgkmcnt(0)
	v_mfma_f32_16x16x32_bf16 v[96:99], v[88:91], v[112:115], v[96:99]
	v_mul_f32_e32 v100, v143, v213
	v_exp_f32_e32 v100, v100
	s_nop 5
	v_mul_f32_e32 v96, v100, v96
	v_cndmask_b32_e64 v96, 0, v96, s[60:61]
	v_cvt_pk_bf16_f32 v96, v96, v131
	ds_write_b16 v185, v96 offset:224
	v_mul_f32_e32 v96, v143, v214
	v_exp_f32_e32 v96, v96
	s_nop 0
	v_mul_f32_e32 v96, v96, v97
	v_cndmask_b32_e64 v96, 0, v96, s[62:63]
	v_cvt_pk_bf16_f32 v96, v96, v131
	ds_write_b16 v185, v96 offset:496
	v_mul_f32_e32 v96, v143, v215
	v_exp_f32_e32 v96, v96
	s_nop 0
	v_mul_f32_e32 v96, v96, v98
	v_cndmask_b32_e64 v96, 0, v96, s[64:65]
	v_cvt_pk_bf16_f32 v96, v96, v131
	ds_write_b16 v185, v96 offset:768
	v_mul_f32_e32 v96, v143, v216
	v_exp_f32_e32 v96, v96
	s_nop 0
	v_mul_f32_e32 v96, v96, v99
	v_cndmask_b32_e64 v96, 0, v96, s[66:67]
	v_cvt_pk_bf16_f32 v96, v96, v131
	s_cbranch_execz .LBB0_425
	s_branch .LBB0_428

.LBB0_423:
	ds_read_b128 v[96:99], v232 offset:21760
	ds_read_b128 v[100:103], v232 offset:21824
	ds_read_b128 v[108:111], v232 offset:21888
	ds_read_b128 v[112:115], v232 offset:21952
	s_waitcnt lgkmcnt(3)
	v_mfma_f32_16x16x32_bf16 v[96:99], v[84:87], v[96:99], 0
	s_waitcnt lgkmcnt(2)
	v_mfma_f32_16x16x32_bf16 v[96:99], v[92:95], v[100:103], v[96:99]
	s_waitcnt lgkmcnt(1)
	v_mfma_f32_16x16x32_bf16 v[96:99], v[80:83], v[108:111], v[96:99]
	s_waitcnt lgkmcnt(0)
	v_mfma_f32_16x16x32_bf16 v[96:99], v[88:91], v[112:115], v[96:99]
	v_mul_f32_e32 v100, v143, v209
	v_exp_f32_e32 v100, v100
	s_nop 5
	v_mul_f32_e32 v96, v100, v96
	v_cndmask_b32_e64 v96, 0, v96, s[52:53]
	v_cvt_pk_bf16_f32 v96, v96, v131
	ds_write_b16 v185, v96 offset:192
	v_mul_f32_e32 v96, v143, v210
	v_exp_f32_e32 v96, v96
	s_nop 0
	v_mul_f32_e32 v96, v96, v97
	v_cndmask_b32_e64 v96, 0, v96, s[54:55]
	v_cvt_pk_bf16_f32 v96, v96, v131
	ds_write_b16 v185, v96 offset:464
	v_mul_f32_e32 v96, v143, v211
	v_exp_f32_e32 v96, v96
	s_nop 0
	v_mul_f32_e32 v96, v96, v98
	v_cndmask_b32_e64 v96, 0, v96, s[56:57]
	v_cvt_pk_bf16_f32 v96, v96, v131
	ds_write_b16 v185, v96 offset:736
	v_mul_f32_e32 v96, v143, v212
	v_exp_f32_e32 v96, v96
	s_nop 0
	v_mul_f32_e32 v96, v96, v99
	v_cndmask_b32_e64 v96, 0, v96, s[58:59]
	v_cvt_pk_bf16_f32 v96, v96, v131
	ds_write_b16 v185, v96 offset:1008
	s_andn2_b64 vcc, exec, s[26:27]
	s_cbranch_vccz .LBB0_421

.LBB0_433:
	ds_read_b128 v[236:239], v233 offset:64
	ds_read_b128 v[240:243], v235 offset:34880
	ds_read_b128 v[244:247], v235 offset:39232
	ds_read_b128 v[252:255], v235 offset:43584
	s_waitcnt lgkmcnt(2)
	v_mfma_f32_16x16x32_bf16 v[116:119], v[236:239], v[240:243], v[116:119]
	ds_read_b128 v[240:243], v235 offset:47936
	s_waitcnt lgkmcnt(2)
	v_mfma_f32_16x16x32_bf16 v[124:127], v[236:239], v[244:247], v[124:127]
	ds_read_b128 v[244:247], v235 offset:52288
	s_waitcnt lgkmcnt(2)
	v_mfma_f32_16x16x32_bf16 v[108:111], v[236:239], v[252:255], v[108:111]
	ds_read_b128 v[252:255], v235 offset:56640
	s_waitcnt lgkmcnt(2)
	v_mfma_f32_16x16x32_bf16 v[120:123], v[236:239], v[240:243], v[120:123]
	ds_read_b128 v[240:243], v235 offset:60992
	s_waitcnt lgkmcnt(2)
	v_mfma_f32_16x16x32_bf16 v[104:107], v[236:239], v[244:247], v[104:107]
	ds_read_b128 v[244:247], v235 offset:65344
	s_waitcnt lgkmcnt(2)
	v_mfma_f32_16x16x32_bf16 v[112:115], v[236:239], v[252:255], v[112:115]
	s_waitcnt lgkmcnt(1)
	v_mfma_f32_16x16x32_bf16 v[96:99], v[236:239], v[240:243], v[96:99]
	s_waitcnt lgkmcnt(0)
	v_mfma_f32_16x16x32_bf16 v[100:103], v[236:239], v[244:247], v[100:103]
	s_and_b64 vcc, exec, s[70:71]
	s_cbranch_vccnz .LBB0_432
.LBB0_434:
	ds_read_b128 v[236:239], v233 offset:128
	ds_read_b128 v[240:243], v235 offset:34944
	ds_read_b128 v[244:247], v235 offset:39296
	ds_read_b128 v[252:255], v235 offset:43648
	s_waitcnt lgkmcnt(2)
	v_mfma_f32_16x16x32_bf16 v[116:119], v[236:239], v[240:243], v[116:119]
	ds_read_b128 v[240:243], v235 offset:48000
	s_waitcnt lgkmcnt(2)
	v_mfma_f32_16x16x32_bf16 v[124:127], v[236:239], v[244:247], v[124:127]
	ds_read_b128 v[244:247], v235 offset:52352
	s_waitcnt lgkmcnt(2)
	v_mfma_f32_16x16x32_bf16 v[108:111], v[236:239], v[252:255], v[108:111]
	ds_read_b128 v[252:255], v235 offset:56704
	s_waitcnt lgkmcnt(2)
	v_mfma_f32_16x16x32_bf16 v[120:123], v[236:239], v[240:243], v[120:123]
	ds_read_b128 v[240:243], v235 offset:61056
	s_waitcnt lgkmcnt(2)
	v_mfma_f32_16x16x32_bf16 v[104:107], v[236:239], v[244:247], v[104:107]
	ds_read_b128 v[244:247], v235 offset:65408
	s_waitcnt lgkmcnt(2)
	v_mfma_f32_16x16x32_bf16 v[112:115], v[236:239], v[252:255], v[112:115]
	s_waitcnt lgkmcnt(1)
	v_mfma_f32_16x16x32_bf16 v[96:99], v[236:239], v[240:243], v[96:99]
	s_waitcnt lgkmcnt(0)
	v_mfma_f32_16x16x32_bf16 v[100:103], v[236:239], v[244:247], v[100:103]
	s_and_b64 vcc, exec, s[72:73]
	s_cbranch_vccnz .LBB0_393
.LBB0_435:
	ds_read_b128 v[236:239], v233 offset:192
	ds_read_b128 v[240:243], v235 offset:35008
	ds_read_b128 v[244:247], v235 offset:39360
	ds_read_b128 v[252:255], v235 offset:43712
	s_waitcnt lgkmcnt(2)
	v_mfma_f32_16x16x32_bf16 v[116:119], v[236:239], v[240:243], v[116:119]
	ds_read_b128 v[240:243], v235 offset:48064
	s_waitcnt lgkmcnt(2)
	v_mfma_f32_16x16x32_bf16 v[124:127], v[236:239], v[244:247], v[124:127]
	ds_read_b128 v[244:247], v235 offset:52416
	s_waitcnt lgkmcnt(2)
	v_mfma_f32_16x16x32_bf16 v[108:111], v[236:239], v[252:255], v[108:111]
	ds_read_b128 v[252:255], v235 offset:56768
	s_waitcnt lgkmcnt(2)
	v_mfma_f32_16x16x32_bf16 v[120:123], v[236:239], v[240:243], v[120:123]
	ds_read_b128 v[240:243], v235 offset:61120
	s_waitcnt lgkmcnt(2)
	v_mfma_f32_16x16x32_bf16 v[104:107], v[236:239], v[244:247], v[104:107]
	ds_read_b128 v[244:247], v235 offset:65472
	s_waitcnt lgkmcnt(2)
	v_mfma_f32_16x16x32_bf16 v[112:115], v[236:239], v[252:255], v[112:115]
	s_waitcnt lgkmcnt(1)
	v_mfma_f32_16x16x32_bf16 v[96:99], v[236:239], v[240:243], v[96:99]
	s_waitcnt lgkmcnt(0)
	v_mfma_f32_16x16x32_bf16 v[100:103], v[236:239], v[244:247], v[100:103]
	s_branch .LBB0_393
